# v160 plus P6 epilogue f32 stores bounced through a per-wave LDS tile in two half-exec rounds so each store writes 8 rows x 128 contiguous bytes
# speedup vs baseline: 1.0276x; 1.0033x over previous
; __device__ __forceinline__ void unpack8(const u32x4 w, float (&f)[8]) { f[0] = bflo(w.x); f[1] = bfhi(w.x); f[2] = bflo(w.y); f[3] = bfhi(w.y); f[4] = bflo(w.z); f[5] = bfhi(w.z); f[6] = bflo(w.w); f[7] = bfhi(w.w); }
;     __device__ __forceinline__ void operator()(const f32x4 (&acc)[2][2][4][2], const Unit& u, int wr, int wc, int fr, int fq) const {
;         const int row0 = u.pm * BM + wr * 64 + fr, col0 = u.pn * BM + wc * 32 + 8 * fq;
; #pragma unroll
;         for (int ai = 0; ai < 2; ++ai)
; #pragma unroll
;             for (int m = 0; m < 4; ++m) { const size_t idx = (size_t)(row0 + ai * HALF + m * 16) * 1024 + col0;
; #pragma unroll
;                 for (int bj = 0; bj < 2; ++bj) { float h[8]; unpack8(__builtin_nontemporal_load((const u32x4*)(h1b + idx + bj * HALF)), h);
;                     const f32x4 a0 = acc[ai][bj][m][0], a1 = acc[ai][bj][m][1];
;                     __builtin_nontemporal_store(((f32x4){h[0] + a0[0], h[1] + a0[1], h[2] + a0[2], h[3] + a0[3]}), (f32x4*)(out + idx + bj * HALF));
;                     __builtin_nontemporal_store(((f32x4){h[4] + a1[0], h[5] + a1[1], h[6] + a1[2], h[7] + a1[3]}), (f32x4*)(out + idx + bj * HALF + 4)); } }
;     }
.LBB0_816:
	v_lshl_add_u32 v232, s28, 8, v150
	v_lshl_or_b32 v233, s47, 8, v152
	v_lshl_add_u32 v232, v232, 10, v233
	v_lshlrev_b32_e32 v232, 1, v232
	global_load_dwordx4 v[156:159], v232, s[8:9] nt
	global_load_dwordx4 v[160:163], v232, s[8:9] offset:256 nt
	v_add_u32_e32 v232, 0x8000, v232
	global_load_dwordx4 v[164:167], v232, s[8:9] nt
	global_load_dwordx4 v[168:171], v232, s[8:9] offset:256 nt
	v_add_u32_e32 v232, 0x8000, v232
	global_load_dwordx4 v[172:175], v232, s[8:9] nt
	global_load_dwordx4 v[176:179], v232, s[8:9] offset:256 nt
	v_add_u32_e32 v232, 0x8000, v232
	global_load_dwordx4 v[180:183], v232, s[8:9] nt
	global_load_dwordx4 v[184:187], v232, s[8:9] offset:256 nt
	v_add_u32_e32 v232, 0x28000, v232
	global_load_dwordx4 v[188:191], v232, s[8:9] nt
	global_load_dwordx4 v[192:195], v232, s[8:9] offset:256 nt
	v_add_u32_e32 v232, 0x8000, v232
	global_load_dwordx4 v[196:199], v232, s[8:9] nt
	global_load_dwordx4 v[200:203], v232, s[8:9] offset:256 nt
	v_add_u32_e32 v232, 0x8000, v232
	global_load_dwordx4 v[204:207], v232, s[8:9] nt
	global_load_dwordx4 v[208:211], v232, s[8:9] offset:256 nt
	v_add_u32_e32 v232, 0x8000, v232
	global_load_dwordx4 v[212:215], v232, s[8:9] nt
	global_load_dwordx4 v[216:219], v232, s[8:9] offset:256 nt
	v_mbcnt_lo_u32_b32 v224, -1, 0
	v_mbcnt_hi_u32_b32 v224, -1, v224
	v_bfe_u32 v225, v150, 6, 1
	v_bfe_u32 v226, v152, 5, 2
	v_lshl_or_b32 v225, v225, 2, v226
	v_lshlrev_b32_e32 v225, 10, v225
	v_add_u32_e32 v225, 0x20000, v225
	v_and_b32_e32 v226, 7, v150
	v_bfe_u32 v227, v152, 3, 2
	v_lshlrev_b32_e32 v227, 1, v227
	v_xor_b32_e32 v228, v227, v226
	v_lshlrev_b32_e32 v228, 4, v228
	v_lshl_add_u32 v234, v226, 7, v228
	v_add_u32_e32 v234, v234, v225
	v_or_b32_e32 v227, 1, v227
	v_xor_b32_e32 v228, v227, v226
	v_lshlrev_b32_e32 v228, 4, v228
	v_lshl_add_u32 v235, v226, 7, v228
	v_add_u32_e32 v235, v235, v225
	v_lshrrev_b32_e32 v226, 3, v224
	v_and_b32_e32 v227, 7, v224
	v_xor_b32_e32 v228, v227, v226
	v_lshlrev_b32_e32 v228, 4, v228
	v_lshl_add_u32 v236, v226, 7, v228
	v_add_u32_e32 v236, v236, v225
	v_and_b32_e32 v228, 0xfffffff0, v150
	v_add_u32_e32 v228, v228, v226
	v_lshl_add_u32 v228, s28, 8, v228
	v_and_b32_e32 v229, 0xffffffe7, v152
	v_lshl_or_b32 v229, s47, 8, v229
	v_lshl_add_u32 v229, v227, 2, v229
	v_lshl_add_u32 v228, v228, 10, v229
	v_lshlrev_b32_e32 v233, 2, v228
	v_add_u32_e32 v237, 0x8000, v233
	s_mov_b32 s98, 0x00ff00ff
	s_mov_b32 s99, 0x00ff00ff
	s_mov_b32 s100, 0xff00ff00
	s_mov_b32 s101, 0xff00ff00
	s_waitcnt vmcnt(14)
	v_lshlrev_b32_e32 v224, 16, v156
	v_and_b32_e32 v225, 0xffff0000, v156
	v_lshlrev_b32_e32 v226, 16, v157
	v_and_b32_e32 v227, 0xffff0000, v157
	v_lshlrev_b32_e32 v228, 16, v158
	v_and_b32_e32 v229, 0xffff0000, v158
	v_lshlrev_b32_e32 v230, 16, v159
	v_and_b32_e32 v231, 0xffff0000, v159
	v_pk_add_f32 v[124:125], v[124:125], v[224:225]
	v_pk_add_f32 v[126:127], v[126:127], v[226:227]
	v_pk_add_f32 v[120:121], v[120:121], v[228:229]
	v_pk_add_f32 v[122:123], v[122:123], v[230:231]
	s_mov_b64 exec, s[98:99]
	ds_write_b128 v234, v[124:127]
	ds_write_b128 v235, v[120:123]
	s_mov_b64 exec, -1
	ds_read_b128 v[238:241], v236
	s_mov_b64 exec, s[100:101]
	ds_write_b128 v234, v[124:127]
	ds_write_b128 v235, v[120:123]
	s_mov_b64 exec, -1
	ds_read_b128 v[242:245], v236
	s_waitcnt lgkmcnt(3)
	global_store_dwordx4 v233, v[238:241], s[50:51] nt
	s_waitcnt lgkmcnt(0)
	global_store_dwordx4 v237, v[242:245], s[50:51] nt
	v_lshlrev_b32_e32 v224, 16, v160
	v_and_b32_e32 v225, 0xffff0000, v160
	v_lshlrev_b32_e32 v226, 16, v161
	v_and_b32_e32 v227, 0xffff0000, v161
	v_lshlrev_b32_e32 v228, 16, v162
	v_and_b32_e32 v229, 0xffff0000, v162
	v_lshlrev_b32_e32 v230, 16, v163
	v_and_b32_e32 v231, 0xffff0000, v163
	v_pk_add_f32 v[116:117], v[116:117], v[224:225]
	v_pk_add_f32 v[118:119], v[118:119], v[226:227]
	v_pk_add_f32 v[112:113], v[112:113], v[228:229]
	v_pk_add_f32 v[114:115], v[114:115], v[230:231]
	s_mov_b64 exec, s[98:99]
	ds_write_b128 v234, v[116:119]
	ds_write_b128 v235, v[112:115]
	s_mov_b64 exec, -1
	ds_read_b128 v[238:241], v236
	s_mov_b64 exec, s[100:101]
	ds_write_b128 v234, v[116:119]
	ds_write_b128 v235, v[112:115]
	s_mov_b64 exec, -1
	ds_read_b128 v[242:245], v236
	s_waitcnt lgkmcnt(3)
	global_store_dwordx4 v233, v[238:241], s[50:51] offset:512 nt
	s_waitcnt lgkmcnt(0)
	global_store_dwordx4 v237, v[242:245], s[50:51] offset:512 nt
	v_add_u32_e32 v233, 0x10000, v233
	v_add_u32_e32 v237, 0x10000, v237
	s_waitcnt vmcnt(16)
	v_lshlrev_b32_e32 v224, 16, v164
	v_and_b32_e32 v225, 0xffff0000, v164
	v_lshlrev_b32_e32 v226, 16, v165
	v_and_b32_e32 v227, 0xffff0000, v165
	v_lshlrev_b32_e32 v228, 16, v166
	v_and_b32_e32 v229, 0xffff0000, v166
	v_lshlrev_b32_e32 v230, 16, v167
	v_and_b32_e32 v231, 0xffff0000, v167
	v_pk_add_f32 v[108:109], v[108:109], v[224:225]
	v_pk_add_f32 v[110:111], v[110:111], v[226:227]
	v_pk_add_f32 v[104:105], v[104:105], v[228:229]
	v_pk_add_f32 v[106:107], v[106:107], v[230:231]
	s_mov_b64 exec, s[98:99]
	ds_write_b128 v234, v[108:111]
	ds_write_b128 v235, v[104:107]
	s_mov_b64 exec, -1
	ds_read_b128 v[238:241], v236
	s_mov_b64 exec, s[100:101]
	ds_write_b128 v234, v[108:111]
	ds_write_b128 v235, v[104:107]
	s_mov_b64 exec, -1
	ds_read_b128 v[242:245], v236
	s_waitcnt lgkmcnt(3)
	global_store_dwordx4 v233, v[238:241], s[50:51] nt
	s_waitcnt lgkmcnt(0)
; __device__ __forceinline__ void unpack8(const u32x4 w, float (&f)[8]) { f[0] = bflo(w.x); f[1] = bfhi(w.x); f[2] = bflo(w.y); f[3] = bfhi(w.y); f[4] = bflo(w.z); f[5] = bfhi(w.z); f[6] = bflo(w.w); f[7] = bfhi(w.w); }
;     __device__ __forceinline__ void operator()(const f32x4 (&acc)[2][2][4][2], const Unit& u, int wr, int wc, int fr, int fq) const {
;         const int row0 = u.pm * BM + wr * 64 + fr, col0 = u.pn * BM + wc * 32 + 8 * fq;
; #pragma unroll
;         for (int ai = 0; ai < 2; ++ai)
; #pragma unroll
;             for (int m = 0; m < 4; ++m) { const size_t idx = (size_t)(row0 + ai * HALF + m * 16) * 1024 + col0;
; #pragma unroll
;                 for (int bj = 0; bj < 2; ++bj) { float h[8]; unpack8(__builtin_nontemporal_load((const u32x4*)(h1b + idx + bj * HALF)), h);
;                     const f32x4 a0 = acc[ai][bj][m][0], a1 = acc[ai][bj][m][1];
;                     __builtin_nontemporal_store(((f32x4){h[0] + a0[0], h[1] + a0[1], h[2] + a0[2], h[3] + a0[3]}), (f32x4*)(out + idx + bj * HALF));
;                     __builtin_nontemporal_store(((f32x4){h[4] + a1[0], h[5] + a1[1], h[6] + a1[2], h[7] + a1[3]}), (f32x4*)(out + idx + bj * HALF + 4)); } }
;     }
	global_store_dwordx4 v237, v[242:245], s[50:51] nt
	v_lshlrev_b32_e32 v224, 16, v168
	v_and_b32_e32 v225, 0xffff0000, v168
	v_lshlrev_b32_e32 v226, 16, v169
	v_and_b32_e32 v227, 0xffff0000, v169
	v_lshlrev_b32_e32 v228, 16, v170
	v_and_b32_e32 v229, 0xffff0000, v170
	v_lshlrev_b32_e32 v230, 16, v171
	v_and_b32_e32 v231, 0xffff0000, v171
	v_pk_add_f32 v[100:101], v[100:101], v[224:225]
	v_pk_add_f32 v[102:103], v[102:103], v[226:227]
	v_pk_add_f32 v[96:97], v[96:97], v[228:229]
	v_pk_add_f32 v[98:99], v[98:99], v[230:231]
	s_mov_b64 exec, s[98:99]
	ds_write_b128 v234, v[100:103]
	ds_write_b128 v235, v[96:99]
	s_mov_b64 exec, -1
	ds_read_b128 v[238:241], v236
	s_mov_b64 exec, s[100:101]
	ds_write_b128 v234, v[100:103]
	ds_write_b128 v235, v[96:99]
	s_mov_b64 exec, -1
	ds_read_b128 v[242:245], v236
	s_waitcnt lgkmcnt(3)
	global_store_dwordx4 v233, v[238:241], s[50:51] offset:512 nt
	s_waitcnt lgkmcnt(0)
	global_store_dwordx4 v237, v[242:245], s[50:51] offset:512 nt
	v_add_u32_e32 v233, 0x10000, v233
	v_add_u32_e32 v237, 0x10000, v237
	s_waitcnt vmcnt(18)
	v_lshlrev_b32_e32 v224, 16, v172
	v_and_b32_e32 v225, 0xffff0000, v172
	v_lshlrev_b32_e32 v226, 16, v173
	v_and_b32_e32 v227, 0xffff0000, v173
	v_lshlrev_b32_e32 v228, 16, v174
	v_and_b32_e32 v229, 0xffff0000, v174
	v_lshlrev_b32_e32 v230, 16, v175
	v_and_b32_e32 v231, 0xffff0000, v175
	v_pk_add_f32 v[92:93], v[92:93], v[224:225]
	v_pk_add_f32 v[94:95], v[94:95], v[226:227]
	v_pk_add_f32 v[88:89], v[88:89], v[228:229]
	v_pk_add_f32 v[90:91], v[90:91], v[230:231]
	s_mov_b64 exec, s[98:99]
	ds_write_b128 v234, v[92:95]
	ds_write_b128 v235, v[88:91]
	s_mov_b64 exec, -1
	ds_read_b128 v[238:241], v236
	s_mov_b64 exec, s[100:101]
	ds_write_b128 v234, v[92:95]
	ds_write_b128 v235, v[88:91]
	s_mov_b64 exec, -1
	ds_read_b128 v[242:245], v236
	s_waitcnt lgkmcnt(3)
	global_store_dwordx4 v233, v[238:241], s[50:51] nt
	s_waitcnt lgkmcnt(0)
	global_store_dwordx4 v237, v[242:245], s[50:51] nt
	v_lshlrev_b32_e32 v224, 16, v176
	v_and_b32_e32 v225, 0xffff0000, v176
	v_lshlrev_b32_e32 v226, 16, v177
	v_and_b32_e32 v227, 0xffff0000, v177
	v_lshlrev_b32_e32 v228, 16, v178
	v_and_b32_e32 v229, 0xffff0000, v178
	v_lshlrev_b32_e32 v230, 16, v179
	v_and_b32_e32 v231, 0xffff0000, v179
	v_pk_add_f32 v[84:85], v[84:85], v[224:225]
	v_pk_add_f32 v[86:87], v[86:87], v[226:227]
	v_pk_add_f32 v[80:81], v[80:81], v[228:229]
	v_pk_add_f32 v[82:83], v[82:83], v[230:231]
	s_mov_b64 exec, s[98:99]
	ds_write_b128 v234, v[84:87]
	ds_write_b128 v235, v[80:83]
	s_mov_b64 exec, -1
	ds_read_b128 v[238:241], v236
	s_mov_b64 exec, s[100:101]
	ds_write_b128 v234, v[84:87]
	ds_write_b128 v235, v[80:83]
	s_mov_b64 exec, -1
	ds_read_b128 v[242:245], v236
	s_waitcnt lgkmcnt(3)
	global_store_dwordx4 v233, v[238:241], s[50:51] offset:512 nt
	s_waitcnt lgkmcnt(0)
	global_store_dwordx4 v237, v[242:245], s[50:51] offset:512 nt
	v_add_u32_e32 v233, 0x10000, v233
	v_add_u32_e32 v237, 0x10000, v237
	s_waitcnt vmcnt(20)
	v_lshlrev_b32_e32 v224, 16, v180
	v_and_b32_e32 v225, 0xffff0000, v180
	v_lshlrev_b32_e32 v226, 16, v181
	v_and_b32_e32 v227, 0xffff0000, v181
	v_lshlrev_b32_e32 v228, 16, v182
	v_and_b32_e32 v229, 0xffff0000, v182
	v_lshlrev_b32_e32 v230, 16, v183
	v_and_b32_e32 v231, 0xffff0000, v183
	v_pk_add_f32 v[76:77], v[76:77], v[224:225]
	v_pk_add_f32 v[78:79], v[78:79], v[226:227]
	v_pk_add_f32 v[72:73], v[72:73], v[228:229]
	v_pk_add_f32 v[74:75], v[74:75], v[230:231]
	s_mov_b64 exec, s[98:99]
	ds_write_b128 v234, v[76:79]
	ds_write_b128 v235, v[72:75]
	s_mov_b64 exec, -1
	ds_read_b128 v[238:241], v236
	s_mov_b64 exec, s[100:101]
	ds_write_b128 v234, v[76:79]
	ds_write_b128 v235, v[72:75]
	s_mov_b64 exec, -1
	ds_read_b128 v[242:245], v236
	s_waitcnt lgkmcnt(3)
	global_store_dwordx4 v233, v[238:241], s[50:51] nt
	s_waitcnt lgkmcnt(0)
	global_store_dwordx4 v237, v[242:245], s[50:51] nt
	v_lshlrev_b32_e32 v224, 16, v184
	v_and_b32_e32 v225, 0xffff0000, v184
	v_lshlrev_b32_e32 v226, 16, v185
	v_and_b32_e32 v227, 0xffff0000, v185
	v_lshlrev_b32_e32 v228, 16, v186
	v_and_b32_e32 v229, 0xffff0000, v186
	v_lshlrev_b32_e32 v230, 16, v187
	v_and_b32_e32 v231, 0xffff0000, v187
	v_pk_add_f32 v[68:69], v[68:69], v[224:225]
	v_pk_add_f32 v[70:71], v[70:71], v[226:227]
	v_pk_add_f32 v[64:65], v[64:65], v[228:229]
	v_pk_add_f32 v[66:67], v[66:67], v[230:231]
	s_mov_b64 exec, s[98:99]
	ds_write_b128 v234, v[68:71]
	ds_write_b128 v235, v[64:67]
	s_mov_b64 exec, -1
	ds_read_b128 v[238:241], v236
	s_mov_b64 exec, s[100:101]
	ds_write_b128 v234, v[68:71]
	ds_write_b128 v235, v[64:67]
	s_mov_b64 exec, -1
	ds_read_b128 v[242:245], v236
	s_waitcnt lgkmcnt(3)
	global_store_dwordx4 v233, v[238:241], s[50:51] offset:512 nt
	s_waitcnt lgkmcnt(0)
	global_store_dwordx4 v237, v[242:245], s[50:51] offset:512 nt
	v_add_u32_e32 v233, 0x50000, v233
	v_add_u32_e32 v237, 0x50000, v237
	s_waitcnt vmcnt(22)
	v_lshlrev_b32_e32 v224, 16, v188
	v_and_b32_e32 v225, 0xffff0000, v188
	v_lshlrev_b32_e32 v226, 16, v189
	v_and_b32_e32 v227, 0xffff0000, v189
	v_lshlrev_b32_e32 v228, 16, v190
	v_and_b32_e32 v229, 0xffff0000, v190
	v_lshlrev_b32_e32 v230, 16, v191
	v_and_b32_e32 v231, 0xffff0000, v191
	v_pk_add_f32 v[60:61], v[60:61], v[224:225]
	v_pk_add_f32 v[62:63], v[62:63], v[226:227]
	v_pk_add_f32 v[56:57], v[56:57], v[228:229]
	v_pk_add_f32 v[58:59], v[58:59], v[230:231]
	s_mov_b64 exec, s[98:99]
	ds_write_b128 v234, v[60:63]
	ds_write_b128 v235, v[56:59]
	s_mov_b64 exec, -1
	ds_read_b128 v[238:241], v236
	s_mov_b64 exec, s[100:101]
	ds_write_b128 v234, v[60:63]
	ds_write_b128 v235, v[56:59]
	s_mov_b64 exec, -1
	ds_read_b128 v[242:245], v236
	s_waitcnt lgkmcnt(3)
; __device__ __forceinline__ void unpack8(const u32x4 w, float (&f)[8]) { f[0] = bflo(w.x); f[1] = bfhi(w.x); f[2] = bflo(w.y); f[3] = bfhi(w.y); f[4] = bflo(w.z); f[5] = bfhi(w.z); f[6] = bflo(w.w); f[7] = bfhi(w.w); }
;     __device__ __forceinline__ void operator()(const f32x4 (&acc)[2][2][4][2], const Unit& u, int wr, int wc, int fr, int fq) const {
;         const int row0 = u.pm * BM + wr * 64 + fr, col0 = u.pn * BM + wc * 32 + 8 * fq;
; #pragma unroll
;         for (int ai = 0; ai < 2; ++ai)
; #pragma unroll
;             for (int m = 0; m < 4; ++m) { const size_t idx = (size_t)(row0 + ai * HALF + m * 16) * 1024 + col0;
; #pragma unroll
;                 for (int bj = 0; bj < 2; ++bj) { float h[8]; unpack8(__builtin_nontemporal_load((const u32x4*)(h1b + idx + bj * HALF)), h);
;                     const f32x4 a0 = acc[ai][bj][m][0], a1 = acc[ai][bj][m][1];
;                     __builtin_nontemporal_store(((f32x4){h[0] + a0[0], h[1] + a0[1], h[2] + a0[2], h[3] + a0[3]}), (f32x4*)(out + idx + bj * HALF));
;                     __builtin_nontemporal_store(((f32x4){h[4] + a1[0], h[5] + a1[1], h[6] + a1[2], h[7] + a1[3]}), (f32x4*)(out + idx + bj * HALF + 4)); } }
;     }
	global_store_dwordx4 v233, v[238:241], s[50:51] nt
	s_waitcnt lgkmcnt(0)
	global_store_dwordx4 v237, v[242:245], s[50:51] nt
	v_lshlrev_b32_e32 v224, 16, v192
	v_and_b32_e32 v225, 0xffff0000, v192
	v_lshlrev_b32_e32 v226, 16, v193
	v_and_b32_e32 v227, 0xffff0000, v193
	v_lshlrev_b32_e32 v228, 16, v194
	v_and_b32_e32 v229, 0xffff0000, v194
	v_lshlrev_b32_e32 v230, 16, v195
	v_and_b32_e32 v231, 0xffff0000, v195
	v_pk_add_f32 v[52:53], v[52:53], v[224:225]
	v_pk_add_f32 v[54:55], v[54:55], v[226:227]
	v_pk_add_f32 v[48:49], v[48:49], v[228:229]
	v_pk_add_f32 v[50:51], v[50:51], v[230:231]
	s_mov_b64 exec, s[98:99]
	ds_write_b128 v234, v[52:55]
	ds_write_b128 v235, v[48:51]
	s_mov_b64 exec, -1
	ds_read_b128 v[238:241], v236
	s_mov_b64 exec, s[100:101]
	ds_write_b128 v234, v[52:55]
	ds_write_b128 v235, v[48:51]
	s_mov_b64 exec, -1
	ds_read_b128 v[242:245], v236
	s_waitcnt lgkmcnt(3)
	global_store_dwordx4 v233, v[238:241], s[50:51] offset:512 nt
	s_waitcnt lgkmcnt(0)
	global_store_dwordx4 v237, v[242:245], s[50:51] offset:512 nt
	v_add_u32_e32 v233, 0x10000, v233
	v_add_u32_e32 v237, 0x10000, v237
	s_waitcnt vmcnt(24)
	v_lshlrev_b32_e32 v224, 16, v196
	v_and_b32_e32 v225, 0xffff0000, v196
	v_lshlrev_b32_e32 v226, 16, v197
	v_and_b32_e32 v227, 0xffff0000, v197
	v_lshlrev_b32_e32 v228, 16, v198
	v_and_b32_e32 v229, 0xffff0000, v198
	v_lshlrev_b32_e32 v230, 16, v199
	v_and_b32_e32 v231, 0xffff0000, v199
	v_pk_add_f32 v[44:45], v[44:45], v[224:225]
	v_pk_add_f32 v[46:47], v[46:47], v[226:227]
	v_pk_add_f32 v[40:41], v[40:41], v[228:229]
	v_pk_add_f32 v[42:43], v[42:43], v[230:231]
	s_mov_b64 exec, s[98:99]
	ds_write_b128 v234, v[44:47]
	ds_write_b128 v235, v[40:43]
	s_mov_b64 exec, -1
	ds_read_b128 v[238:241], v236
	s_mov_b64 exec, s[100:101]
	ds_write_b128 v234, v[44:47]
	ds_write_b128 v235, v[40:43]
	s_mov_b64 exec, -1
	ds_read_b128 v[242:245], v236
	s_waitcnt lgkmcnt(3)
	global_store_dwordx4 v233, v[238:241], s[50:51] nt
	s_waitcnt lgkmcnt(0)
	global_store_dwordx4 v237, v[242:245], s[50:51] nt
	v_lshlrev_b32_e32 v224, 16, v200
	v_and_b32_e32 v225, 0xffff0000, v200
	v_lshlrev_b32_e32 v226, 16, v201
	v_and_b32_e32 v227, 0xffff0000, v201
	v_lshlrev_b32_e32 v228, 16, v202
	v_and_b32_e32 v229, 0xffff0000, v202
	v_lshlrev_b32_e32 v230, 16, v203
	v_and_b32_e32 v231, 0xffff0000, v203
	v_pk_add_f32 v[36:37], v[36:37], v[224:225]
	v_pk_add_f32 v[38:39], v[38:39], v[226:227]
	v_pk_add_f32 v[32:33], v[32:33], v[228:229]
	v_pk_add_f32 v[34:35], v[34:35], v[230:231]
	s_mov_b64 exec, s[98:99]
	ds_write_b128 v234, v[36:39]
	ds_write_b128 v235, v[32:35]
	s_mov_b64 exec, -1
	ds_read_b128 v[238:241], v236
	s_mov_b64 exec, s[100:101]
	ds_write_b128 v234, v[36:39]
	ds_write_b128 v235, v[32:35]
	s_mov_b64 exec, -1
	ds_read_b128 v[242:245], v236
	s_waitcnt lgkmcnt(3)
	global_store_dwordx4 v233, v[238:241], s[50:51] offset:512 nt
	s_waitcnt lgkmcnt(0)
	global_store_dwordx4 v237, v[242:245], s[50:51] offset:512 nt
	v_add_u32_e32 v233, 0x10000, v233
	v_add_u32_e32 v237, 0x10000, v237
	s_waitcnt vmcnt(26)
	v_lshlrev_b32_e32 v224, 16, v204
	v_and_b32_e32 v225, 0xffff0000, v204
	v_lshlrev_b32_e32 v226, 16, v205
	v_and_b32_e32 v227, 0xffff0000, v205
	v_lshlrev_b32_e32 v228, 16, v206
	v_and_b32_e32 v229, 0xffff0000, v206
	v_lshlrev_b32_e32 v230, 16, v207
	v_and_b32_e32 v231, 0xffff0000, v207
	v_pk_add_f32 v[28:29], v[28:29], v[224:225]
	v_pk_add_f32 v[30:31], v[30:31], v[226:227]
	v_pk_add_f32 v[24:25], v[24:25], v[228:229]
	v_pk_add_f32 v[26:27], v[26:27], v[230:231]
	s_mov_b64 exec, s[98:99]
	ds_write_b128 v234, v[28:31]
	ds_write_b128 v235, v[24:27]
	s_mov_b64 exec, -1
	ds_read_b128 v[238:241], v236
	s_mov_b64 exec, s[100:101]
	ds_write_b128 v234, v[28:31]
	ds_write_b128 v235, v[24:27]
	s_mov_b64 exec, -1
	ds_read_b128 v[242:245], v236
	s_waitcnt lgkmcnt(3)
	global_store_dwordx4 v233, v[238:241], s[50:51] nt
	s_waitcnt lgkmcnt(0)
	global_store_dwordx4 v237, v[242:245], s[50:51] nt
	v_lshlrev_b32_e32 v224, 16, v208
	v_and_b32_e32 v225, 0xffff0000, v208
	v_lshlrev_b32_e32 v226, 16, v209
	v_and_b32_e32 v227, 0xffff0000, v209
	v_lshlrev_b32_e32 v228, 16, v210
	v_and_b32_e32 v229, 0xffff0000, v210
	v_lshlrev_b32_e32 v230, 16, v211
	v_and_b32_e32 v231, 0xffff0000, v211
	v_pk_add_f32 v[20:21], v[20:21], v[224:225]
	v_pk_add_f32 v[22:23], v[22:23], v[226:227]
	v_pk_add_f32 v[16:17], v[16:17], v[228:229]
	v_pk_add_f32 v[18:19], v[18:19], v[230:231]
	s_mov_b64 exec, s[98:99]
	ds_write_b128 v234, v[20:23]
	ds_write_b128 v235, v[16:19]
	s_mov_b64 exec, -1
	ds_read_b128 v[238:241], v236
	s_mov_b64 exec, s[100:101]
	ds_write_b128 v234, v[20:23]
	ds_write_b128 v235, v[16:19]
	s_mov_b64 exec, -1
	ds_read_b128 v[242:245], v236
	s_waitcnt lgkmcnt(3)
	global_store_dwordx4 v233, v[238:241], s[50:51] offset:512 nt
	s_waitcnt lgkmcnt(0)
	global_store_dwordx4 v237, v[242:245], s[50:51] offset:512 nt
	v_add_u32_e32 v233, 0x10000, v233
	v_add_u32_e32 v237, 0x10000, v237
	s_waitcnt vmcnt(28)
	v_lshlrev_b32_e32 v224, 16, v212
	v_and_b32_e32 v225, 0xffff0000, v212
	v_lshlrev_b32_e32 v226, 16, v213
	v_and_b32_e32 v227, 0xffff0000, v213
	v_lshlrev_b32_e32 v228, 16, v214
	v_and_b32_e32 v229, 0xffff0000, v214
	v_lshlrev_b32_e32 v230, 16, v215
	v_and_b32_e32 v231, 0xffff0000, v215
	v_pk_add_f32 v[12:13], v[12:13], v[224:225]
	v_pk_add_f32 v[14:15], v[14:15], v[226:227]
	v_pk_add_f32 v[8:9], v[8:9], v[228:229]
	v_pk_add_f32 v[10:11], v[10:11], v[230:231]
	s_mov_b64 exec, s[98:99]
	ds_write_b128 v234, v[12:15]
	ds_write_b128 v235, v[8:11]
	s_mov_b64 exec, -1
	ds_read_b128 v[238:241], v236
	s_mov_b64 exec, s[100:101]
	ds_write_b128 v234, v[12:15]
	ds_write_b128 v235, v[8:11]
	s_mov_b64 exec, -1
	ds_read_b128 v[242:245], v236
	s_waitcnt lgkmcnt(3)
	global_store_dwordx4 v233, v[238:241], s[50:51] nt
	s_waitcnt lgkmcnt(0)
	global_store_dwordx4 v237, v[242:245], s[50:51] nt
	v_lshlrev_b32_e32 v224, 16, v216
	v_and_b32_e32 v225, 0xffff0000, v216
	v_lshlrev_b32_e32 v226, 16, v217
	v_and_b32_e32 v227, 0xffff0000, v217
	v_lshlrev_b32_e32 v228, 16, v218
	v_and_b32_e32 v229, 0xffff0000, v218
	v_lshlrev_b32_e32 v230, 16, v219
	v_and_b32_e32 v231, 0xffff0000, v219
	v_pk_add_f32 v[4:5], v[4:5], v[224:225]
	v_pk_add_f32 v[6:7], v[6:7], v[226:227]
	v_pk_add_f32 v[0:1], v[0:1], v[228:229]
	v_pk_add_f32 v[2:3], v[2:3], v[230:231]
	s_mov_b64 exec, s[98:99]
	ds_write_b128 v234, v[4:7]
	ds_write_b128 v235, v[0:3]
	s_mov_b64 exec, -1
	ds_read_b128 v[238:241], v236
	s_mov_b64 exec, s[100:101]
	ds_write_b128 v234, v[4:7]
	ds_write_b128 v235, v[0:3]
	s_mov_b64 exec, -1
	ds_read_b128 v[242:245], v236
	s_waitcnt lgkmcnt(3)
	global_store_dwordx4 v233, v[238:241], s[50:51] offset:512 nt
	s_waitcnt lgkmcnt(0)
	global_store_dwordx4 v237, v[242:245], s[50:51] offset:512 nt
	s_andn2_b64 vcc, exec, s[0:1]
	s_mov_b64 s[0:1], -1
	s_cbranch_vccnz .LBB0_805
	s_andn2_b64 vcc, exec, s[4:5]
	s_cbranch_vccnz .LBB0_804
	s_barrier
	s_branch .LBB0_804
